# FFN-in epilogue straight-line (8 interleaved chains, no nops); accumulator zeroing with 64-bit moves
# speedup vs baseline: 1.0599x; 1.0047x over previous
.LBB0_205:
	s_ashr_i32 s43, s42, 31
	s_lshl_b64 s[6:7], s[42:43], 19
	v_readlane_b32 s14, v252, 47
	v_readlane_b32 s15, v252, 48
	s_add_u32 s44, s14, s6
	s_addc_u32 s45, s15, s7
	s_and_b64 s[6:7], s[38:39], exec
	s_cselect_b32 s43, s45, s49
	s_cselect_b32 s73, s44, s48
	s_ashr_i32 s41, s40, 31
	s_lshl_b64 s[6:7], s[40:41], 19
	s_add_u32 s46, s16, s6
	s_addc_u32 s47, s17, s7
	s_and_b64 s[6:7], s[38:39], exec
	s_cselect_b32 s75, s47, s13
	s_cselect_b32 s88, s46, s12
	s_lshl_b32 s41, s1, 8
	s_add_u32 s6, s12, 0x100
	v_lshl_add_u32 v169, s10, 8, v3
	s_movk_i32 s0, 0x1300
	s_addc_u32 s7, s13, 0
	v_mul_lo_u32 v170, v169, s0
	s_add_u32 s0, s48, 0x40080
	s_addc_u32 s1, s49, 0
	v_mov_b32_e32 v4, 0
	v_add_u32_e32 v171, s41, v166
	v_add_u32_e32 v168, 0x13000, v170
	v_lshl_add_u64 v[160:161], s[0:1], 0, v[146:147]
	v_lshl_add_u64 v[162:163], s[0:1], 0, v[158:159]
	s_mov_b32 s0, -2
	s_mov_b64 s[50:51], 0
	s_waitcnt lgkmcnt(0)
	s_waitcnt lgkmcnt(0)
	v_mov_b64_e32 v[4:5], 0
	v_mov_b64_e32 v[6:7], 0
	v_mov_b64_e32 v[8:9], 0
	v_mov_b64_e32 v[10:11], 0
	v_mov_b64_e32 v[12:13], 0
	v_mov_b64_e32 v[14:15], 0
	v_mov_b64_e32 v[16:17], 0
	v_mov_b64_e32 v[18:19], 0
	v_mov_b64_e32 v[20:21], 0
	v_mov_b64_e32 v[22:23], 0
	v_mov_b64_e32 v[24:25], 0
	v_mov_b64_e32 v[26:27], 0
	v_mov_b64_e32 v[28:29], 0
	v_mov_b64_e32 v[30:31], 0
	v_mov_b64_e32 v[32:33], 0
	v_mov_b64_e32 v[34:35], 0
	v_mov_b64_e32 v[36:37], 0
	v_mov_b64_e32 v[38:39], 0
	v_mov_b64_e32 v[40:41], 0
	v_mov_b64_e32 v[42:43], 0
	v_mov_b64_e32 v[44:45], 0
	v_mov_b64_e32 v[46:47], 0
	v_mov_b64_e32 v[48:49], 0
	v_mov_b64_e32 v[50:51], 0
	v_mov_b64_e32 v[52:53], 0
	v_mov_b64_e32 v[54:55], 0
	v_mov_b64_e32 v[56:57], 0
	v_mov_b64_e32 v[58:59], 0
	v_mov_b64_e32 v[60:61], 0
	v_mov_b64_e32 v[62:63], 0
	v_mov_b64_e32 v[64:65], 0
	v_mov_b64_e32 v[66:67], 0
	v_mov_b64_e32 v[68:69], 0
	v_mov_b64_e32 v[70:71], 0
	v_mov_b64_e32 v[72:73], 0
	v_mov_b64_e32 v[74:75], 0
	v_mov_b64_e32 v[76:77], 0
	v_mov_b64_e32 v[78:79], 0
	v_mov_b64_e32 v[80:81], 0
	v_mov_b64_e32 v[82:83], 0
	v_mov_b64_e32 v[84:85], 0
	v_mov_b64_e32 v[86:87], 0
	v_mov_b64_e32 v[88:89], 0
	v_mov_b64_e32 v[90:91], 0
	v_mov_b64_e32 v[92:93], 0
	v_mov_b64_e32 v[94:95], 0
	v_mov_b64_e32 v[96:97], 0
	v_mov_b64_e32 v[98:99], 0
	v_mov_b64_e32 v[100:101], 0
	v_mov_b64_e32 v[102:103], 0
	v_mov_b64_e32 v[104:105], 0
	v_mov_b64_e32 v[106:107], 0
	v_mov_b64_e32 v[108:109], 0
	v_mov_b64_e32 v[110:111], 0
	v_mov_b64_e32 v[112:113], 0
	v_mov_b64_e32 v[114:115], 0
	v_mov_b64_e32 v[116:117], 0
	v_mov_b64_e32 v[118:119], 0
	v_mov_b64_e32 v[120:121], 0
	v_mov_b64_e32 v[122:123], 0
	v_mov_b64_e32 v[124:125], 0
	v_mov_b64_e32 v[126:127], 0
	v_mov_b64_e32 v[128:129], 0
	v_mov_b64_e32 v[130:131], 0
	s_branch .LBB0_207

.LBB0_436:
	s_ashr_i32 s11, s10, 31
	s_lshl_b64 s[4:5], s[10:11], 19
	s_add_u32 s4, s19, s4
	s_addc_u32 s5, s53, s5
	s_and_b64 s[6:7], s[38:39], exec
	s_cselect_b32 s3, s5, s15
	s_cselect_b32 s11, s4, s14
	s_ashr_i32 s9, s8, 31
	s_lshl_b64 s[6:7], s[8:9], 19
	s_add_u32 s6, s54, s6
	s_addc_u32 s7, s55, s7
	s_and_b64 s[16:17], s[38:39], exec
	s_cselect_b32 s9, s7, s13
	s_cselect_b32 s22, s6, s12
	s_add_u32 s23, s12, 0x100
	s_addc_u32 s24, s13, 0
	s_add_u32 s12, s14, 0x40080
	v_mov_b32_e32 v4, 0
	s_addc_u32 s13, s15, 0
	s_mov_b32 s27, -2
	s_waitcnt lgkmcnt(0)
	s_waitcnt lgkmcnt(0)
	v_mov_b64_e32 v[4:5], 0
	v_mov_b64_e32 v[6:7], 0
	v_mov_b64_e32 v[8:9], 0
	v_mov_b64_e32 v[10:11], 0
	v_mov_b64_e32 v[12:13], 0
	v_mov_b64_e32 v[14:15], 0
	v_mov_b64_e32 v[16:17], 0
	v_mov_b64_e32 v[18:19], 0
	v_mov_b64_e32 v[20:21], 0
	v_mov_b64_e32 v[22:23], 0
	v_mov_b64_e32 v[24:25], 0
	v_mov_b64_e32 v[26:27], 0
	v_mov_b64_e32 v[28:29], 0
	v_mov_b64_e32 v[30:31], 0
	v_mov_b64_e32 v[32:33], 0
	v_mov_b64_e32 v[34:35], 0
	v_mov_b64_e32 v[36:37], 0
	v_mov_b64_e32 v[38:39], 0
	v_mov_b64_e32 v[40:41], 0
	v_mov_b64_e32 v[42:43], 0
	v_mov_b64_e32 v[44:45], 0
	v_mov_b64_e32 v[46:47], 0
	v_mov_b64_e32 v[48:49], 0
	v_mov_b64_e32 v[50:51], 0
	v_mov_b64_e32 v[52:53], 0
	v_mov_b64_e32 v[54:55], 0
	v_mov_b64_e32 v[56:57], 0
	v_mov_b64_e32 v[58:59], 0
	v_mov_b64_e32 v[60:61], 0
	v_mov_b64_e32 v[62:63], 0
	v_mov_b64_e32 v[64:65], 0
	v_mov_b64_e32 v[66:67], 0
	v_mov_b64_e32 v[68:69], 0
	v_mov_b64_e32 v[70:71], 0
	v_mov_b64_e32 v[72:73], 0
	v_mov_b64_e32 v[74:75], 0
	v_mov_b64_e32 v[76:77], 0
	v_mov_b64_e32 v[78:79], 0
	v_mov_b64_e32 v[80:81], 0
	v_mov_b64_e32 v[82:83], 0
	v_mov_b64_e32 v[84:85], 0
	v_mov_b64_e32 v[86:87], 0
	v_mov_b64_e32 v[88:89], 0
	v_mov_b64_e32 v[90:91], 0
	v_mov_b64_e32 v[92:93], 0
	v_mov_b64_e32 v[94:95], 0
	v_mov_b64_e32 v[96:97], 0
	v_mov_b64_e32 v[98:99], 0
	v_mov_b64_e32 v[100:101], 0
	v_mov_b64_e32 v[102:103], 0
	v_mov_b64_e32 v[104:105], 0
	v_mov_b64_e32 v[106:107], 0
	v_mov_b64_e32 v[108:109], 0
	v_mov_b64_e32 v[110:111], 0
	v_mov_b64_e32 v[112:113], 0
	v_mov_b64_e32 v[114:115], 0
	v_mov_b64_e32 v[116:117], 0
	v_mov_b64_e32 v[118:119], 0
	v_mov_b64_e32 v[120:121], 0
	v_mov_b64_e32 v[122:123], 0
	v_mov_b64_e32 v[124:125], 0
	v_mov_b64_e32 v[126:127], 0
	v_mov_b64_e32 v[128:129], 0
	v_mov_b64_e32 v[130:131], 0

.LBB0_619:
	s_ashr_i32 s41, s40, 31
	s_lshl_b64 s[16:17], s[40:41], 19
	s_add_u32 s42, s48, s16
	s_addc_u32 s43, s49, s17
	s_and_b64 s[16:17], s[38:39], exec
	s_cselect_b32 s11, s43, s47
	s_cselect_b32 s22, s42, s46
	s_ashr_i32 s9, s8, 31
	s_lshl_b64 s[16:17], s[8:9], 19
	s_add_u32 s44, s50, s16
	s_addc_u32 s45, s51, s17
	s_and_b64 s[16:17], s[38:39], exec
	s_cselect_b32 s9, s45, s15
	s_cselect_b32 s28, s44, s14
	s_add_u32 s23, s14, 0x100
	s_addc_u32 s24, s15, 0
	s_add_u32 s14, s46, 0x40080
	v_mov_b32_e32 v4, 0
	s_addc_u32 s15, s47, 0
	s_mov_b32 s27, -2
	s_waitcnt lgkmcnt(0)
	s_waitcnt lgkmcnt(0)
	v_mov_b64_e32 v[4:5], 0
	v_mov_b64_e32 v[6:7], 0
	v_mov_b64_e32 v[8:9], 0
	v_mov_b64_e32 v[10:11], 0
	v_mov_b64_e32 v[12:13], 0
	v_mov_b64_e32 v[14:15], 0
	v_mov_b64_e32 v[16:17], 0
	v_mov_b64_e32 v[18:19], 0
	v_mov_b64_e32 v[20:21], 0
	v_mov_b64_e32 v[22:23], 0
	v_mov_b64_e32 v[24:25], 0
	v_mov_b64_e32 v[26:27], 0
	v_mov_b64_e32 v[28:29], 0
	v_mov_b64_e32 v[30:31], 0
	v_mov_b64_e32 v[32:33], 0
	v_mov_b64_e32 v[34:35], 0
	v_mov_b64_e32 v[36:37], 0
	v_mov_b64_e32 v[38:39], 0
	v_mov_b64_e32 v[40:41], 0
	v_mov_b64_e32 v[42:43], 0
	v_mov_b64_e32 v[44:45], 0
	v_mov_b64_e32 v[46:47], 0
	v_mov_b64_e32 v[48:49], 0
	v_mov_b64_e32 v[50:51], 0
	v_mov_b64_e32 v[52:53], 0
	v_mov_b64_e32 v[54:55], 0
	v_mov_b64_e32 v[56:57], 0
	v_mov_b64_e32 v[58:59], 0
	v_mov_b64_e32 v[60:61], 0
	v_mov_b64_e32 v[62:63], 0
	v_mov_b64_e32 v[64:65], 0
	v_mov_b64_e32 v[66:67], 0
	v_mov_b64_e32 v[68:69], 0
	v_mov_b64_e32 v[70:71], 0
	v_mov_b64_e32 v[72:73], 0
	v_mov_b64_e32 v[74:75], 0
	v_mov_b64_e32 v[76:77], 0
	v_mov_b64_e32 v[78:79], 0
	v_mov_b64_e32 v[80:81], 0
	v_mov_b64_e32 v[82:83], 0
	v_mov_b64_e32 v[84:85], 0
	v_mov_b64_e32 v[86:87], 0
	v_mov_b64_e32 v[88:89], 0
	v_mov_b64_e32 v[90:91], 0
	v_mov_b64_e32 v[92:93], 0
	v_mov_b64_e32 v[94:95], 0
	v_mov_b64_e32 v[96:97], 0
	v_mov_b64_e32 v[98:99], 0
	v_mov_b64_e32 v[100:101], 0
	v_mov_b64_e32 v[102:103], 0
	v_mov_b64_e32 v[104:105], 0
	v_mov_b64_e32 v[106:107], 0
	v_mov_b64_e32 v[108:109], 0
	v_mov_b64_e32 v[110:111], 0
	v_mov_b64_e32 v[112:113], 0
	v_mov_b64_e32 v[114:115], 0
	v_mov_b64_e32 v[116:117], 0
	v_mov_b64_e32 v[118:119], 0
	v_mov_b64_e32 v[120:121], 0
	v_mov_b64_e32 v[122:123], 0
	v_mov_b64_e32 v[124:125], 0
	v_mov_b64_e32 v[126:127], 0
	v_mov_b64_e32 v[128:129], 0
	v_mov_b64_e32 v[130:131], 0

.LBB0_623:
	v_lshl_or_b32 v161, s10, 7, v147
	v_lshl_add_u32 v159, s12, 8, v3
	s_movk_i32 s9, 0x1600
	v_mul_lo_u32 v160, v159, s9
	v_lshl_add_u32 v160, v161, 1, v160
	s_andn2_b64 vcc, exec, s[38:39]
	s_mov_b32 s23, 0xffff
	s_mov_b32 s19, s69
	s_mov_b64 s[10:11], -1
	v_mul_f32_e32 v162, 0xbfb8aa3b, v128
	v_mul_f32_e32 v163, 0xbfb8aa3b, v129
	v_mul_f32_e32 v164, 0xbfb8aa3b, v130
	v_mul_f32_e32 v165, 0xbfb8aa3b, v131
	v_mul_f32_e32 v166, 0xbfb8aa3b, v120
	v_mul_f32_e32 v167, 0xbfb8aa3b, v121
	v_mul_f32_e32 v168, 0xbfb8aa3b, v122
	v_mul_f32_e32 v169, 0xbfb8aa3b, v123
	v_exp_f32_e32 v162, v162
	v_exp_f32_e32 v163, v163
	v_exp_f32_e32 v164, v164
	v_exp_f32_e32 v165, v165
	v_exp_f32_e32 v166, v166
	v_exp_f32_e32 v167, v167
	v_exp_f32_e32 v168, v168
	v_exp_f32_e32 v169, v169
	v_add_f32_e32 v162, 1.0, v162
	v_add_f32_e32 v163, 1.0, v163
	v_add_f32_e32 v164, 1.0, v164
	v_add_f32_e32 v165, 1.0, v165
	v_add_f32_e32 v166, 1.0, v166
	v_add_f32_e32 v167, 1.0, v167
	v_add_f32_e32 v168, 1.0, v168
	v_add_f32_e32 v169, 1.0, v169
	v_rcp_f32_e32 v162, v162
	v_rcp_f32_e32 v163, v163
	v_rcp_f32_e32 v164, v164
	v_rcp_f32_e32 v165, v165
	v_rcp_f32_e32 v166, v166
	v_rcp_f32_e32 v167, v167
	v_rcp_f32_e32 v168, v168
	v_rcp_f32_e32 v169, v169
	v_mul_f32_e32 v162, v128, v162
	v_mul_f32_e32 v163, v129, v163
	v_mul_f32_e32 v164, v130, v164
	v_mul_f32_e32 v165, v131, v165
	v_mul_f32_e32 v166, v120, v166
	v_mul_f32_e32 v167, v121, v167
	v_mul_f32_e32 v168, v122, v168
	v_mul_f32_e32 v169, v123, v169
	v_mul_f32_e32 v124, v124, v162
	v_mul_f32_e32 v125, v125, v163
	v_mul_f32_e32 v126, v126, v164
	v_mul_f32_e32 v127, v127, v165
	v_mul_f32_e32 v116, v116, v166
	v_mul_f32_e32 v117, v117, v167
	v_mul_f32_e32 v118, v118, v168
	v_mul_f32_e32 v119, v119, v169
	v_cvt_pk_bf16_f32 v124, v124, v125
	v_cvt_pk_bf16_f32 v125, v126, v127
	v_cvt_pk_bf16_f32 v126, v116, v117
	v_cvt_pk_bf16_f32 v127, v118, v119
	global_store_dwordx4 v160, v[124:127], s[4:5]
	v_add_u32_e32 v160, 0x16000, v160
	v_mul_f32_e32 v162, 0xbfb8aa3b, v112
	v_mul_f32_e32 v163, 0xbfb8aa3b, v113
	v_mul_f32_e32 v164, 0xbfb8aa3b, v114
	v_mul_f32_e32 v165, 0xbfb8aa3b, v115
	v_mul_f32_e32 v166, 0xbfb8aa3b, v104
	v_mul_f32_e32 v167, 0xbfb8aa3b, v105
	v_mul_f32_e32 v168, 0xbfb8aa3b, v106
	v_mul_f32_e32 v169, 0xbfb8aa3b, v107
	v_exp_f32_e32 v162, v162
	v_exp_f32_e32 v163, v163
	v_exp_f32_e32 v164, v164
	v_exp_f32_e32 v165, v165
	v_exp_f32_e32 v166, v166
	v_exp_f32_e32 v167, v167
	v_exp_f32_e32 v168, v168
	v_exp_f32_e32 v169, v169
	v_add_f32_e32 v162, 1.0, v162
	v_add_f32_e32 v163, 1.0, v163
	v_add_f32_e32 v164, 1.0, v164
	v_add_f32_e32 v165, 1.0, v165
	v_add_f32_e32 v166, 1.0, v166
	v_add_f32_e32 v167, 1.0, v167
	v_add_f32_e32 v168, 1.0, v168
	v_add_f32_e32 v169, 1.0, v169
	v_rcp_f32_e32 v162, v162
	v_rcp_f32_e32 v163, v163
	v_rcp_f32_e32 v164, v164
	v_rcp_f32_e32 v165, v165
	v_rcp_f32_e32 v166, v166
	v_rcp_f32_e32 v167, v167
	v_rcp_f32_e32 v168, v168
	v_rcp_f32_e32 v169, v169
	v_mul_f32_e32 v162, v112, v162
	v_mul_f32_e32 v163, v113, v163
	v_mul_f32_e32 v164, v114, v164
	v_mul_f32_e32 v165, v115, v165
	v_mul_f32_e32 v166, v104, v166
	v_mul_f32_e32 v167, v105, v167
	v_mul_f32_e32 v168, v106, v168
	v_mul_f32_e32 v169, v107, v169
	v_mul_f32_e32 v108, v108, v162
	v_mul_f32_e32 v109, v109, v163
	v_mul_f32_e32 v110, v110, v164
	v_mul_f32_e32 v111, v111, v165
	v_mul_f32_e32 v100, v100, v166
	v_mul_f32_e32 v101, v101, v167
	v_mul_f32_e32 v102, v102, v168
	v_mul_f32_e32 v103, v103, v169
	v_cvt_pk_bf16_f32 v108, v108, v109
	v_cvt_pk_bf16_f32 v109, v110, v111
	v_cvt_pk_bf16_f32 v110, v100, v101
	v_cvt_pk_bf16_f32 v111, v102, v103
	global_store_dwordx4 v160, v[108:111], s[4:5]
	v_add_u32_e32 v160, 0x16000, v160
	v_mul_f32_e32 v162, 0xbfb8aa3b, v96
	v_mul_f32_e32 v163, 0xbfb8aa3b, v97
	v_mul_f32_e32 v164, 0xbfb8aa3b, v98
	v_mul_f32_e32 v165, 0xbfb8aa3b, v99
	v_mul_f32_e32 v166, 0xbfb8aa3b, v88
	v_mul_f32_e32 v167, 0xbfb8aa3b, v89
	v_mul_f32_e32 v168, 0xbfb8aa3b, v90
	v_mul_f32_e32 v169, 0xbfb8aa3b, v91
	v_exp_f32_e32 v162, v162
	v_exp_f32_e32 v163, v163
	v_exp_f32_e32 v164, v164
	v_exp_f32_e32 v165, v165
	v_exp_f32_e32 v166, v166
	v_exp_f32_e32 v167, v167
	v_exp_f32_e32 v168, v168
	v_exp_f32_e32 v169, v169
	v_add_f32_e32 v162, 1.0, v162
	v_add_f32_e32 v163, 1.0, v163
	v_add_f32_e32 v164, 1.0, v164
	v_add_f32_e32 v165, 1.0, v165
	v_add_f32_e32 v166, 1.0, v166
	v_add_f32_e32 v167, 1.0, v167
	v_add_f32_e32 v168, 1.0, v168
	v_add_f32_e32 v169, 1.0, v169
	v_rcp_f32_e32 v162, v162
	v_rcp_f32_e32 v163, v163
	v_rcp_f32_e32 v164, v164
	v_rcp_f32_e32 v165, v165
	v_rcp_f32_e32 v166, v166
	v_rcp_f32_e32 v167, v167
	v_rcp_f32_e32 v168, v168
	v_rcp_f32_e32 v169, v169
	v_mul_f32_e32 v162, v96, v162
	v_mul_f32_e32 v163, v97, v163
	v_mul_f32_e32 v164, v98, v164
	v_mul_f32_e32 v165, v99, v165
	v_mul_f32_e32 v166, v88, v166
	v_mul_f32_e32 v167, v89, v167
	v_mul_f32_e32 v168, v90, v168
	v_mul_f32_e32 v169, v91, v169
	v_mul_f32_e32 v92, v92, v162
	v_mul_f32_e32 v93, v93, v163
	v_mul_f32_e32 v94, v94, v164
	v_mul_f32_e32 v95, v95, v165
	v_mul_f32_e32 v84, v84, v166
	v_mul_f32_e32 v85, v85, v167
	v_mul_f32_e32 v86, v86, v168
	v_mul_f32_e32 v87, v87, v169
	v_cvt_pk_bf16_f32 v92, v92, v93
	v_cvt_pk_bf16_f32 v93, v94, v95
	v_cvt_pk_bf16_f32 v94, v84, v85
	v_cvt_pk_bf16_f32 v95, v86, v87
	global_store_dwordx4 v160, v[92:95], s[4:5]
	v_add_u32_e32 v160, 0x16000, v160
	v_mul_f32_e32 v162, 0xbfb8aa3b, v80
	v_mul_f32_e32 v163, 0xbfb8aa3b, v81
	v_mul_f32_e32 v164, 0xbfb8aa3b, v82
	v_mul_f32_e32 v165, 0xbfb8aa3b, v83
	v_mul_f32_e32 v166, 0xbfb8aa3b, v72
	v_mul_f32_e32 v167, 0xbfb8aa3b, v73
	v_mul_f32_e32 v168, 0xbfb8aa3b, v74
	v_mul_f32_e32 v169, 0xbfb8aa3b, v75
	v_exp_f32_e32 v162, v162
	v_exp_f32_e32 v163, v163
	v_exp_f32_e32 v164, v164
	v_exp_f32_e32 v165, v165
	v_exp_f32_e32 v166, v166
	v_exp_f32_e32 v167, v167
	v_exp_f32_e32 v168, v168
	v_exp_f32_e32 v169, v169
	v_add_f32_e32 v162, 1.0, v162
	v_add_f32_e32 v163, 1.0, v163
	v_add_f32_e32 v164, 1.0, v164
	v_add_f32_e32 v165, 1.0, v165
	v_add_f32_e32 v166, 1.0, v166
	v_add_f32_e32 v167, 1.0, v167
	v_add_f32_e32 v168, 1.0, v168
	v_add_f32_e32 v169, 1.0, v169
	v_rcp_f32_e32 v162, v162
	v_rcp_f32_e32 v163, v163
	v_rcp_f32_e32 v164, v164
	v_rcp_f32_e32 v165, v165
	v_rcp_f32_e32 v166, v166
	v_rcp_f32_e32 v167, v167
	v_rcp_f32_e32 v168, v168
	v_rcp_f32_e32 v169, v169
	v_mul_f32_e32 v162, v80, v162
	v_mul_f32_e32 v163, v81, v163
	v_mul_f32_e32 v164, v82, v164
	v_mul_f32_e32 v165, v83, v165
	v_mul_f32_e32 v166, v72, v166
	v_mul_f32_e32 v167, v73, v167
	v_mul_f32_e32 v168, v74, v168
	v_mul_f32_e32 v169, v75, v169
	v_mul_f32_e32 v76, v76, v162
	v_mul_f32_e32 v77, v77, v163
	v_mul_f32_e32 v78, v78, v164
	v_mul_f32_e32 v79, v79, v165
	v_mul_f32_e32 v68, v68, v166
	v_mul_f32_e32 v69, v69, v167
	v_mul_f32_e32 v70, v70, v168
	v_mul_f32_e32 v71, v71, v169
	v_cvt_pk_bf16_f32 v76, v76, v77
	v_cvt_pk_bf16_f32 v77, v78, v79
	v_cvt_pk_bf16_f32 v78, v68, v69
	v_cvt_pk_bf16_f32 v79, v70, v71
	global_store_dwordx4 v160, v[76:79], s[4:5]
	v_add_u32_e32 v160, 0x6e000, v160
	v_mul_f32_e32 v162, 0xbfb8aa3b, v64
	v_mul_f32_e32 v163, 0xbfb8aa3b, v65
	v_mul_f32_e32 v164, 0xbfb8aa3b, v66
	v_mul_f32_e32 v165, 0xbfb8aa3b, v67
	v_mul_f32_e32 v166, 0xbfb8aa3b, v56
	v_mul_f32_e32 v167, 0xbfb8aa3b, v57
	v_mul_f32_e32 v168, 0xbfb8aa3b, v58
	v_mul_f32_e32 v169, 0xbfb8aa3b, v59
	v_exp_f32_e32 v162, v162
	v_exp_f32_e32 v163, v163
	v_exp_f32_e32 v164, v164
	v_exp_f32_e32 v165, v165
	v_exp_f32_e32 v166, v166
	v_exp_f32_e32 v167, v167
	v_exp_f32_e32 v168, v168
	v_exp_f32_e32 v169, v169
	v_add_f32_e32 v162, 1.0, v162
	v_add_f32_e32 v163, 1.0, v163
	v_add_f32_e32 v164, 1.0, v164
	v_add_f32_e32 v165, 1.0, v165
	v_add_f32_e32 v166, 1.0, v166
	v_add_f32_e32 v167, 1.0, v167
	v_add_f32_e32 v168, 1.0, v168
	v_add_f32_e32 v169, 1.0, v169
	v_rcp_f32_e32 v162, v162
	v_rcp_f32_e32 v163, v163
	v_rcp_f32_e32 v164, v164
	v_rcp_f32_e32 v165, v165
	v_rcp_f32_e32 v166, v166
	v_rcp_f32_e32 v167, v167
	v_rcp_f32_e32 v168, v168
	v_rcp_f32_e32 v169, v169
	v_mul_f32_e32 v162, v64, v162
	v_mul_f32_e32 v163, v65, v163
	v_mul_f32_e32 v164, v66, v164
	v_mul_f32_e32 v165, v67, v165
	v_mul_f32_e32 v166, v56, v166
	v_mul_f32_e32 v167, v57, v167
	v_mul_f32_e32 v168, v58, v168
	v_mul_f32_e32 v169, v59, v169
	v_mul_f32_e32 v60, v60, v162
	v_mul_f32_e32 v61, v61, v163
	v_mul_f32_e32 v62, v62, v164
	v_mul_f32_e32 v63, v63, v165
	v_mul_f32_e32 v52, v52, v166
	v_mul_f32_e32 v53, v53, v167
	v_mul_f32_e32 v54, v54, v168
	v_mul_f32_e32 v55, v55, v169
	v_cvt_pk_bf16_f32 v60, v60, v61
	v_cvt_pk_bf16_f32 v61, v62, v63
	v_cvt_pk_bf16_f32 v62, v52, v53
	v_cvt_pk_bf16_f32 v63, v54, v55
	global_store_dwordx4 v160, v[60:63], s[4:5]
	v_add_u32_e32 v160, 0x16000, v160
	v_mul_f32_e32 v162, 0xbfb8aa3b, v48
	v_mul_f32_e32 v163, 0xbfb8aa3b, v49
	v_mul_f32_e32 v164, 0xbfb8aa3b, v50
	v_mul_f32_e32 v165, 0xbfb8aa3b, v51
	v_mul_f32_e32 v166, 0xbfb8aa3b, v40
	v_mul_f32_e32 v167, 0xbfb8aa3b, v41
	v_mul_f32_e32 v168, 0xbfb8aa3b, v42
	v_mul_f32_e32 v169, 0xbfb8aa3b, v43
	v_exp_f32_e32 v162, v162
	v_exp_f32_e32 v163, v163
	v_exp_f32_e32 v164, v164
	v_exp_f32_e32 v165, v165
	v_exp_f32_e32 v166, v166
	v_exp_f32_e32 v167, v167
	v_exp_f32_e32 v168, v168
	v_exp_f32_e32 v169, v169
	v_add_f32_e32 v162, 1.0, v162
	v_add_f32_e32 v163, 1.0, v163
	v_add_f32_e32 v164, 1.0, v164
	v_add_f32_e32 v165, 1.0, v165
	v_add_f32_e32 v166, 1.0, v166
	v_add_f32_e32 v167, 1.0, v167
	v_add_f32_e32 v168, 1.0, v168
	v_add_f32_e32 v169, 1.0, v169
	v_rcp_f32_e32 v162, v162
	v_rcp_f32_e32 v163, v163
	v_rcp_f32_e32 v164, v164
	v_rcp_f32_e32 v165, v165
	v_rcp_f32_e32 v166, v166
	v_rcp_f32_e32 v167, v167
	v_rcp_f32_e32 v168, v168
	v_rcp_f32_e32 v169, v169
	v_mul_f32_e32 v162, v48, v162
	v_mul_f32_e32 v163, v49, v163
	v_mul_f32_e32 v164, v50, v164
	v_mul_f32_e32 v165, v51, v165
	v_mul_f32_e32 v166, v40, v166
	v_mul_f32_e32 v167, v41, v167
	v_mul_f32_e32 v168, v42, v168
	v_mul_f32_e32 v169, v43, v169
	v_mul_f32_e32 v44, v44, v162
	v_mul_f32_e32 v45, v45, v163
	v_mul_f32_e32 v46, v46, v164
	v_mul_f32_e32 v47, v47, v165
	v_mul_f32_e32 v36, v36, v166
	v_mul_f32_e32 v37, v37, v167
	v_mul_f32_e32 v38, v38, v168
	v_mul_f32_e32 v39, v39, v169
	v_cvt_pk_bf16_f32 v44, v44, v45
	v_cvt_pk_bf16_f32 v45, v46, v47
	v_cvt_pk_bf16_f32 v46, v36, v37
	v_cvt_pk_bf16_f32 v47, v38, v39
	global_store_dwordx4 v160, v[44:47], s[4:5]
	v_add_u32_e32 v160, 0x16000, v160
	v_mul_f32_e32 v162, 0xbfb8aa3b, v32
	v_mul_f32_e32 v163, 0xbfb8aa3b, v33
	v_mul_f32_e32 v164, 0xbfb8aa3b, v34
	v_mul_f32_e32 v165, 0xbfb8aa3b, v35
	v_mul_f32_e32 v166, 0xbfb8aa3b, v24
	v_mul_f32_e32 v167, 0xbfb8aa3b, v25
	v_mul_f32_e32 v168, 0xbfb8aa3b, v26
	v_mul_f32_e32 v169, 0xbfb8aa3b, v27
	v_exp_f32_e32 v162, v162
	v_exp_f32_e32 v163, v163
	v_exp_f32_e32 v164, v164
	v_exp_f32_e32 v165, v165
	v_exp_f32_e32 v166, v166
	v_exp_f32_e32 v167, v167
	v_exp_f32_e32 v168, v168
	v_exp_f32_e32 v169, v169
	v_add_f32_e32 v162, 1.0, v162
	v_add_f32_e32 v163, 1.0, v163
	v_add_f32_e32 v164, 1.0, v164
	v_add_f32_e32 v165, 1.0, v165
	v_add_f32_e32 v166, 1.0, v166
	v_add_f32_e32 v167, 1.0, v167
	v_add_f32_e32 v168, 1.0, v168
	v_add_f32_e32 v169, 1.0, v169
	v_rcp_f32_e32 v162, v162
	v_rcp_f32_e32 v163, v163
	v_rcp_f32_e32 v164, v164
	v_rcp_f32_e32 v165, v165
	v_rcp_f32_e32 v166, v166
	v_rcp_f32_e32 v167, v167
	v_rcp_f32_e32 v168, v168
	v_rcp_f32_e32 v169, v169
	v_mul_f32_e32 v162, v32, v162
	v_mul_f32_e32 v163, v33, v163
	v_mul_f32_e32 v164, v34, v164
	v_mul_f32_e32 v165, v35, v165
	v_mul_f32_e32 v166, v24, v166
	v_mul_f32_e32 v167, v25, v167
	v_mul_f32_e32 v168, v26, v168
	v_mul_f32_e32 v169, v27, v169
	v_mul_f32_e32 v28, v28, v162
	v_mul_f32_e32 v29, v29, v163
	v_mul_f32_e32 v30, v30, v164
	v_mul_f32_e32 v31, v31, v165
	v_mul_f32_e32 v20, v20, v166
	v_mul_f32_e32 v21, v21, v167
	v_mul_f32_e32 v22, v22, v168
	v_mul_f32_e32 v23, v23, v169
	v_cvt_pk_bf16_f32 v28, v28, v29
	v_cvt_pk_bf16_f32 v29, v30, v31
	v_cvt_pk_bf16_f32 v30, v20, v21
	v_cvt_pk_bf16_f32 v31, v22, v23
	global_store_dwordx4 v160, v[28:31], s[4:5]
	v_add_u32_e32 v160, 0x16000, v160
	v_mul_f32_e32 v162, 0xbfb8aa3b, v16
	v_mul_f32_e32 v163, 0xbfb8aa3b, v17
	v_mul_f32_e32 v164, 0xbfb8aa3b, v18
	v_mul_f32_e32 v165, 0xbfb8aa3b, v19
	v_mul_f32_e32 v166, 0xbfb8aa3b, v8
	v_mul_f32_e32 v167, 0xbfb8aa3b, v9
	v_mul_f32_e32 v168, 0xbfb8aa3b, v10
	v_mul_f32_e32 v169, 0xbfb8aa3b, v11
	v_exp_f32_e32 v162, v162
	v_exp_f32_e32 v163, v163
	v_exp_f32_e32 v164, v164
	v_exp_f32_e32 v165, v165
	v_exp_f32_e32 v166, v166
	v_exp_f32_e32 v167, v167
	v_exp_f32_e32 v168, v168
	v_exp_f32_e32 v169, v169
	v_add_f32_e32 v162, 1.0, v162
	v_add_f32_e32 v163, 1.0, v163
	v_add_f32_e32 v164, 1.0, v164
	v_add_f32_e32 v165, 1.0, v165
	v_add_f32_e32 v166, 1.0, v166
	v_add_f32_e32 v167, 1.0, v167
	v_add_f32_e32 v168, 1.0, v168
	v_add_f32_e32 v169, 1.0, v169
	v_rcp_f32_e32 v162, v162
	v_rcp_f32_e32 v163, v163
	v_rcp_f32_e32 v164, v164
	v_rcp_f32_e32 v165, v165
	v_rcp_f32_e32 v166, v166
	v_rcp_f32_e32 v167, v167
	v_rcp_f32_e32 v168, v168
	v_rcp_f32_e32 v169, v169
	v_mul_f32_e32 v162, v16, v162
	v_mul_f32_e32 v163, v17, v163
	v_mul_f32_e32 v164, v18, v164
	v_mul_f32_e32 v165, v19, v165
	v_mul_f32_e32 v166, v8, v166
	v_mul_f32_e32 v167, v9, v167
	v_mul_f32_e32 v168, v10, v168
	v_mul_f32_e32 v169, v11, v169
	v_mul_f32_e32 v12, v12, v162
	v_mul_f32_e32 v13, v13, v163
	v_mul_f32_e32 v14, v14, v164
	v_mul_f32_e32 v15, v15, v165
	v_mul_f32_e32 v4, v4, v166
	v_mul_f32_e32 v5, v5, v167
	v_mul_f32_e32 v6, v6, v168
	v_mul_f32_e32 v7, v7, v169
	v_cvt_pk_bf16_f32 v12, v12, v13
	v_cvt_pk_bf16_f32 v13, v14, v15
	v_cvt_pk_bf16_f32 v14, v4, v5
	v_cvt_pk_bf16_f32 v15, v6, v7
	global_store_dwordx4 v160, v[12:15], s[4:5]
	s_cbranch_vccnz .LBB0_613
	s_andn2_b64 vcc, exec, s[0:1]
	s_cbranch_vccnz .LBB0_612
	s_barrier
	s_branch .LBB0_612

.LBB0_675:
	s_add_i32 s14, s17, -2
	s_add_u32 s15, s10, 0x100
	s_addc_u32 s23, s11, 0
	s_add_u32 s10, s12, 0x80
	v_mov_b32_e32 v4, 0
	s_addc_u32 s11, s13, 0
	s_mov_b32 s12, 0
	s_waitcnt lgkmcnt(0)
	s_waitcnt lgkmcnt(0)
	v_mov_b64_e32 v[4:5], 0
	v_mov_b64_e32 v[6:7], 0
	v_mov_b64_e32 v[8:9], 0
	v_mov_b64_e32 v[10:11], 0
	v_mov_b64_e32 v[12:13], 0
	v_mov_b64_e32 v[14:15], 0
	v_mov_b64_e32 v[16:17], 0
	v_mov_b64_e32 v[18:19], 0
	v_mov_b64_e32 v[20:21], 0
	v_mov_b64_e32 v[22:23], 0
	v_mov_b64_e32 v[24:25], 0
	v_mov_b64_e32 v[26:27], 0
	v_mov_b64_e32 v[28:29], 0
	v_mov_b64_e32 v[30:31], 0
	v_mov_b64_e32 v[32:33], 0
	v_mov_b64_e32 v[34:35], 0
	v_mov_b64_e32 v[36:37], 0
	v_mov_b64_e32 v[38:39], 0
	v_mov_b64_e32 v[40:41], 0
	v_mov_b64_e32 v[42:43], 0
	v_mov_b64_e32 v[44:45], 0
	v_mov_b64_e32 v[46:47], 0
	v_mov_b64_e32 v[48:49], 0
	v_mov_b64_e32 v[50:51], 0
	v_mov_b64_e32 v[52:53], 0
	v_mov_b64_e32 v[54:55], 0
	v_mov_b64_e32 v[56:57], 0
	v_mov_b64_e32 v[58:59], 0
	v_mov_b64_e32 v[60:61], 0
	v_mov_b64_e32 v[62:63], 0
	v_mov_b64_e32 v[64:65], 0
	v_mov_b64_e32 v[66:67], 0
	v_mov_b64_e32 v[68:69], 0
	v_mov_b64_e32 v[70:71], 0
	v_mov_b64_e32 v[72:73], 0
	v_mov_b64_e32 v[74:75], 0
	v_mov_b64_e32 v[76:77], 0
	v_mov_b64_e32 v[78:79], 0
	v_mov_b64_e32 v[80:81], 0
	v_mov_b64_e32 v[82:83], 0
	v_mov_b64_e32 v[84:85], 0
	v_mov_b64_e32 v[86:87], 0
	v_mov_b64_e32 v[88:89], 0
	v_mov_b64_e32 v[90:91], 0
	v_mov_b64_e32 v[92:93], 0
	v_mov_b64_e32 v[94:95], 0
	v_mov_b64_e32 v[96:97], 0
	v_mov_b64_e32 v[98:99], 0
	v_mov_b64_e32 v[100:101], 0
	v_mov_b64_e32 v[102:103], 0
	v_mov_b64_e32 v[104:105], 0
	v_mov_b64_e32 v[106:107], 0
	v_mov_b64_e32 v[108:109], 0
	v_mov_b64_e32 v[110:111], 0
	v_mov_b64_e32 v[112:113], 0
	v_mov_b64_e32 v[114:115], 0
	v_mov_b64_e32 v[116:117], 0
	v_mov_b64_e32 v[118:119], 0
	v_mov_b64_e32 v[120:121], 0
	v_mov_b64_e32 v[122:123], 0
	v_mov_b64_e32 v[124:125], 0
	v_mov_b64_e32 v[126:127], 0
	v_mov_b64_e32 v[140:141], 0
	v_mov_b64_e32 v[142:143], 0

.LBB0_765:
	s_ashr_i32 s59, s58, 31
	s_lshl_b64 s[16:17], s[58:59], 19
	s_add_u32 s18, s88, s16
	s_addc_u32 s19, s79, s17
	s_and_b64 s[16:17], s[54:55], exec
	s_cselect_b32 s59, s19, s11
	s_cselect_b32 s74, s18, s10
	s_ashr_i32 s9, s8, 31
	s_lshl_b64 s[16:17], s[8:9], 19
	v_readlane_b32 s0, v252, 47
	v_readlane_b32 s1, v252, 48
	s_add_u32 s16, s0, s16
	s_addc_u32 s17, s1, s17
	s_and_b64 vcc, s[54:55], exec
	s_cselect_b32 s9, s17, s13
	s_cselect_b32 s23, s16, s12
	s_add_u32 s24, s12, 0x100
	s_addc_u32 s27, s13, 0
	s_add_u32 vcc_lo, s10, 0x40080
	v_mov_b32_e32 v4, 0
	s_addc_u32 vcc_hi, s11, 0
	s_mov_b32 s77, -2
	v_mov_b64_e32 v[4:5], 0
	v_mov_b64_e32 v[6:7], 0
	v_mov_b64_e32 v[8:9], 0
	v_mov_b64_e32 v[10:11], 0
	v_mov_b64_e32 v[12:13], 0
	v_mov_b64_e32 v[14:15], 0
	v_mov_b64_e32 v[16:17], 0
	v_mov_b64_e32 v[18:19], 0
	v_mov_b64_e32 v[20:21], 0
	v_mov_b64_e32 v[22:23], 0
	v_mov_b64_e32 v[24:25], 0
	v_mov_b64_e32 v[26:27], 0
	v_mov_b64_e32 v[28:29], 0
	v_mov_b64_e32 v[30:31], 0
	v_mov_b64_e32 v[32:33], 0
	v_mov_b64_e32 v[34:35], 0
	v_mov_b64_e32 v[36:37], 0
	v_mov_b64_e32 v[38:39], 0
	v_mov_b64_e32 v[40:41], 0
	v_mov_b64_e32 v[42:43], 0
	v_mov_b64_e32 v[44:45], 0
	v_mov_b64_e32 v[46:47], 0
	v_mov_b64_e32 v[48:49], 0
	v_mov_b64_e32 v[50:51], 0
	v_mov_b64_e32 v[52:53], 0
	v_mov_b64_e32 v[54:55], 0
	v_mov_b64_e32 v[56:57], 0
	v_mov_b64_e32 v[58:59], 0
	v_mov_b64_e32 v[60:61], 0
	v_mov_b64_e32 v[62:63], 0
	v_mov_b64_e32 v[64:65], 0
	v_mov_b64_e32 v[66:67], 0
	v_mov_b64_e32 v[68:69], 0
	v_mov_b64_e32 v[70:71], 0
	v_mov_b64_e32 v[72:73], 0
	v_mov_b64_e32 v[74:75], 0
	v_mov_b64_e32 v[76:77], 0
	v_mov_b64_e32 v[78:79], 0
	v_mov_b64_e32 v[80:81], 0
	v_mov_b64_e32 v[82:83], 0
	v_mov_b64_e32 v[84:85], 0
	v_mov_b64_e32 v[86:87], 0
	v_mov_b64_e32 v[88:89], 0
	v_mov_b64_e32 v[90:91], 0
	v_mov_b64_e32 v[92:93], 0
	v_mov_b64_e32 v[94:95], 0
	v_mov_b64_e32 v[96:97], 0
	v_mov_b64_e32 v[98:99], 0
	v_mov_b64_e32 v[100:101], 0
	v_mov_b64_e32 v[102:103], 0
	v_mov_b64_e32 v[104:105], 0
	v_mov_b64_e32 v[106:107], 0
	v_mov_b64_e32 v[108:109], 0
	v_mov_b64_e32 v[110:111], 0
	v_mov_b64_e32 v[112:113], 0
	v_mov_b64_e32 v[114:115], 0
	v_mov_b64_e32 v[116:117], 0
	v_mov_b64_e32 v[118:119], 0
	v_mov_b64_e32 v[120:121], 0
	v_mov_b64_e32 v[122:123], 0
	v_mov_b64_e32 v[124:125], 0
	v_mov_b64_e32 v[126:127], 0
	v_mov_b64_e32 v[128:129], 0
	v_mov_b64_e32 v[130:131], 0
